# finish phase and norm0 rows: waits count every younger VMEM op in issue order (previous item's stores no longer drained)
# baseline (speedup 1.0000x reference)
; DI void norm0_phase(const P& p, unsigned char* smem) {
;     ...
;         const int row = rt * 16 + wave * 2 + rr;
;         const float* h = row < NLAT ? p.x + (size_t)row * DM : p.ctx + (size_t)(row - NLAT) * DM;
;         const int mr = row < NLAT ? (row >> 11) : 4;
;         f32x4 v[8]; float ss = 0.f;
; #pragma unroll
;         for (int i = 0; i < 8; ++i) { v[i] = __builtin_nontemporal_load((const f32x4*)(h + i * 256 + lane * 4)); ss += v[i][0] * v[i][0] + v[i][1] * v[i][1] + v[i][2] * v[i][2] + v[i][3] * v[i][3]; }
;         ss = wave_sum(ss);
;         const float rstd = rsqrtf(ss * (1.f / 2048.f) + 1e-6f);
;         const float* md = mod + (size_t)mr * 6144;
; #pragma unroll
;         for (int i = 0; i < 8; ++i) {
;             const int j = i * 256 + lane * 4;
;             const f32x4 gw = *(const f32x4*)(p.norm_pre + j), sh = *(const f32x4*)(md + j), scl = *(const f32x4*)(md + 2048 + j);
;             float o[4];
; #pragma unroll
;             for (int e = 0; e < 4; ++e) o[e] = v[i][e] * rstd * gw[e] * (1.f + scl[e]) + sh[e];
;             u32x2 w; w.x = pk2(o[0], o[1]); w.y = pk2(o[2], o[3]);
;             *(u32x2*)(nb + (size_t)row * DM + j) = w;
;         }
.LBB0_97:
	s_lshl_b32 s24, s28, 4
	v_add_u32_e32 v79, s24, v69
	v_ashrrev_i32_e32 v0, 11, v79
	v_mul_hi_i32_i24_e32 v61, 0x6000, v0
	v_mul_i32_i24_e32 v60, 0x6000, v0
	s_mov_b64 s[18:19], -1
	v_and_b32_e32 v4, 63, v166
	v_readfirstlane_b32 s20, v69
	v_lshlrev_b32_e32 v0, 4, v4
	v_lshlrev_b32_e32 v2, 3, v4
	v_add_u32_e32 v1, 0x1000, v0
	v_add_u32_e32 v3, 0x1000, v2
	s_add_u32 s20, s24, s20
	s_lshr_b32 s25, s20, 11
	s_cmpk_ge_u32 s20, 0x2000
	s_cselect_b32 s25, 4, s25
	s_mul_i32 s25, s25, 0x6000
	s_add_u32 s22, s8, s25
	s_addc_u32 s23, s9, 0
	s_add_u32 s48, s22, 0x2000
	s_addc_u32 s49, s23, 0
	s_lshl_b32 s25, s20, 12
	s_add_u32 s26, s10, s25
	s_addc_u32 s27, s11, 0
	global_load_dwordx4 v[80:83], v0, s[6:7] offset:0
	global_load_dwordx4 v[84:87], v0, s[6:7] offset:1024
	global_load_dwordx4 v[88:91], v0, s[6:7] offset:2048
	global_load_dwordx4 v[92:95], v0, s[6:7] offset:3072
	global_load_dwordx4 v[96:99], v1, s[6:7] offset:0
	global_load_dwordx4 v[100:103], v1, s[6:7] offset:1024
	global_load_dwordx4 v[104:107], v1, s[6:7] offset:2048
	global_load_dwordx4 v[108:111], v1, s[6:7] offset:3072
	global_load_dwordx4 v[168:171], v0, s[22:23] offset:0
	global_load_dwordx4 v[200:203], v0, s[48:49] offset:0
	global_load_dwordx4 v[172:175], v0, s[22:23] offset:1024
	global_load_dwordx4 v[204:207], v0, s[48:49] offset:1024
	global_load_dwordx4 v[176:179], v0, s[22:23] offset:2048
	global_load_dwordx4 v[208:211], v0, s[48:49] offset:2048
	global_load_dwordx4 v[180:183], v0, s[22:23] offset:3072
	global_load_dwordx4 v[212:215], v0, s[48:49] offset:3072
	global_load_dwordx4 v[184:187], v1, s[22:23] offset:0
	global_load_dwordx4 v[216:219], v1, s[48:49] offset:0
	global_load_dwordx4 v[188:191], v1, s[22:23] offset:1024
	global_load_dwordx4 v[220:223], v1, s[48:49] offset:1024
	global_load_dwordx4 v[192:195], v1, s[22:23] offset:2048
	global_load_dwordx4 v[224:227], v1, s[48:49] offset:2048
	global_load_dwordx4 v[196:199], v1, s[22:23] offset:3072
	global_load_dwordx4 v[228:231], v1, s[48:49] offset:3072
	s_waitcnt vmcnt(24)
	v_mul_f32_e32 v4, v112, v112
	v_mul_f32_e32 v5, v113, v113
	v_fmac_f32_e32 v4, v114, v114
	v_fmac_f32_e32 v5, v115, v115
	v_fmac_f32_e32 v4, v116, v116
	v_fmac_f32_e32 v5, v117, v117
	v_fmac_f32_e32 v4, v118, v118
	v_fmac_f32_e32 v5, v119, v119
	v_fmac_f32_e32 v4, v120, v120
	v_fmac_f32_e32 v5, v121, v121
	v_fmac_f32_e32 v4, v122, v122
	v_fmac_f32_e32 v5, v123, v123
	v_fmac_f32_e32 v4, v124, v124
	v_fmac_f32_e32 v5, v125, v125
	v_fmac_f32_e32 v4, v126, v126
	v_fmac_f32_e32 v5, v127, v127
	v_fmac_f32_e32 v4, v128, v128
	v_fmac_f32_e32 v5, v129, v129
	v_fmac_f32_e32 v4, v130, v130
	v_fmac_f32_e32 v5, v131, v131
	v_fmac_f32_e32 v4, v132, v132
	v_fmac_f32_e32 v5, v133, v133
	v_fmac_f32_e32 v4, v134, v134
	v_fmac_f32_e32 v5, v135, v135
	v_fmac_f32_e32 v4, v136, v136
	v_fmac_f32_e32 v5, v137, v137
	v_fmac_f32_e32 v4, v138, v138
	v_fmac_f32_e32 v5, v139, v139
	v_fmac_f32_e32 v4, v140, v140
	v_fmac_f32_e32 v5, v141, v141
	v_fmac_f32_e32 v4, v142, v142
	v_fmac_f32_e32 v5, v143, v143
	v_add_f32_e32 v4, v4, v5
	v_mul_f32_e32 v6, v144, v144
	v_mul_f32_e32 v7, v145, v145
	v_fmac_f32_e32 v6, v146, v146
	v_fmac_f32_e32 v7, v147, v147
	v_fmac_f32_e32 v6, v148, v148
	v_fmac_f32_e32 v7, v149, v149
	v_fmac_f32_e32 v6, v150, v150
	v_fmac_f32_e32 v7, v151, v151
	v_fmac_f32_e32 v6, v152, v152
	v_fmac_f32_e32 v7, v153, v153
	v_fmac_f32_e32 v6, v154, v154
	v_fmac_f32_e32 v7, v155, v155
	v_fmac_f32_e32 v6, v156, v156
	v_fmac_f32_e32 v7, v157, v157
	v_fmac_f32_e32 v6, v158, v158
	v_fmac_f32_e32 v7, v159, v159
	v_fmac_f32_e32 v6, v160, v160
	v_fmac_f32_e32 v7, v161, v161
	v_fmac_f32_e32 v6, v162, v162
	v_fmac_f32_e32 v7, v163, v163
	v_fmac_f32_e32 v6, v232, v232
	v_fmac_f32_e32 v7, v233, v233
	v_fmac_f32_e32 v6, v234, v234
	v_fmac_f32_e32 v7, v235, v235
	v_fmac_f32_e32 v6, v236, v236
	v_fmac_f32_e32 v7, v237, v237
	v_fmac_f32_e32 v6, v238, v238
	v_fmac_f32_e32 v7, v239, v239
	v_fmac_f32_e32 v6, v240, v240
	v_fmac_f32_e32 v7, v241, v241
	v_fmac_f32_e32 v6, v242, v242
	v_fmac_f32_e32 v7, v243, v243
	v_add_f32_e32 v6, v6, v7
	ds_bpermute_b32 v8, v72, v4
	ds_bpermute_b32 v9, v72, v6
	s_waitcnt lgkmcnt(1)
	v_add_f32_e32 v4, v4, v8
	s_waitcnt lgkmcnt(0)
	v_add_f32_e32 v6, v6, v9
	ds_bpermute_b32 v8, v73, v4
	ds_bpermute_b32 v9, v73, v6
	s_waitcnt lgkmcnt(1)
	v_add_f32_e32 v4, v4, v8
	s_waitcnt lgkmcnt(0)
	v_add_f32_e32 v6, v6, v9
	ds_bpermute_b32 v8, v74, v4
	ds_bpermute_b32 v9, v74, v6
	s_waitcnt lgkmcnt(1)
	v_add_f32_e32 v4, v4, v8
	s_waitcnt lgkmcnt(0)
	v_add_f32_e32 v6, v6, v9
	ds_bpermute_b32 v8, v75, v4
	ds_bpermute_b32 v9, v75, v6
	s_waitcnt lgkmcnt(1)
	v_add_f32_e32 v4, v4, v8
	s_waitcnt lgkmcnt(0)
	v_add_f32_e32 v6, v6, v9
	ds_bpermute_b32 v8, v76, v4
	ds_bpermute_b32 v9, v76, v6
	s_waitcnt lgkmcnt(1)
	v_add_f32_e32 v4, v4, v8
	s_waitcnt lgkmcnt(0)
	v_add_f32_e32 v6, v6, v9
	ds_bpermute_b32 v8, v77, v4
	ds_bpermute_b32 v9, v77, v6
	s_waitcnt lgkmcnt(1)
	v_add_f32_e32 v4, v4, v8
	s_waitcnt lgkmcnt(0)
	v_add_f32_e32 v6, v6, v9
	v_fmamk_f32 v4, v4, 0x3a000000, v78
	v_fmamk_f32 v6, v6, 0x3a000000, v78
	v_rsq_f32_e32 v10, v4
	v_rsq_f32_e32 v11, v6
	s_waitcnt vmcnt(16)
	v_mul_f32_e32 v12, v112, v10
	v_mul_f32_e32 v13, v113, v10
	v_mul_f32_e32 v14, v114, v10
	v_mul_f32_e32 v15, v115, v10
	v_mul_f32_e32 v12, v12, v80
	v_mul_f32_e32 v13, v13, v81
	v_mul_f32_e32 v14, v14, v82
	v_mul_f32_e32 v15, v15, v83
	s_waitcnt vmcnt(14)
; DI void norm0_phase(const P& p, unsigned char* smem) {
;     ...
; #pragma unroll
;         for (int i = 0; i < 8; ++i) {
;             const int j = i * 256 + lane * 4;
;             const f32x4 gw = *(const f32x4*)(p.norm_pre + j), sh = *(const f32x4*)(md + j), scl = *(const f32x4*)(md + 2048 + j);
;             float o[4];
; #pragma unroll
;             for (int e = 0; e < 4; ++e) o[e] = v[i][e] * rstd * gw[e] * (1.f + scl[e]) + sh[e];
;             u32x2 w; w.x = pk2(o[0], o[1]); w.y = pk2(o[2], o[3]);
;             *(u32x2*)(nb + (size_t)row * DM + j) = w;
;         }
	v_add_f32_e32 v16, 1.0, v200
	v_add_f32_e32 v17, 1.0, v201
	v_add_f32_e32 v18, 1.0, v202
	v_add_f32_e32 v19, 1.0, v203
	v_fma_f32 v12, v12, v16, v168
	v_fma_f32 v13, v13, v17, v169
	v_fma_f32 v14, v14, v18, v170
	v_fma_f32 v15, v15, v19, v171
	v_cvt_pk_bf16_f32 v20, v12, v13
	v_cvt_pk_bf16_f32 v21, v14, v15
	global_store_dwordx2 v2, v[20:21], s[26:27] offset:0
	v_mul_f32_e32 v12, v116, v10
	v_mul_f32_e32 v13, v117, v10
	v_mul_f32_e32 v14, v118, v10
	v_mul_f32_e32 v15, v119, v10
	v_mul_f32_e32 v12, v12, v84
	v_mul_f32_e32 v13, v13, v85
	v_mul_f32_e32 v14, v14, v86
	v_mul_f32_e32 v15, v15, v87
	s_waitcnt vmcnt(13)
	v_add_f32_e32 v16, 1.0, v204
	v_add_f32_e32 v17, 1.0, v205
	v_add_f32_e32 v18, 1.0, v206
	v_add_f32_e32 v19, 1.0, v207
	v_fma_f32 v12, v12, v16, v172
	v_fma_f32 v13, v13, v17, v173
	v_fma_f32 v14, v14, v18, v174
	v_fma_f32 v15, v15, v19, v175
	v_cvt_pk_bf16_f32 v22, v12, v13
	v_cvt_pk_bf16_f32 v23, v14, v15
	global_store_dwordx2 v2, v[22:23], s[26:27] offset:512
	v_mul_f32_e32 v12, v120, v10
	v_mul_f32_e32 v13, v121, v10
	v_mul_f32_e32 v14, v122, v10
	v_mul_f32_e32 v15, v123, v10
	v_mul_f32_e32 v12, v12, v88
	v_mul_f32_e32 v13, v13, v89
	v_mul_f32_e32 v14, v14, v90
	v_mul_f32_e32 v15, v15, v91
	s_waitcnt vmcnt(12)
	v_add_f32_e32 v16, 1.0, v208
	v_add_f32_e32 v17, 1.0, v209
	v_add_f32_e32 v18, 1.0, v210
	v_add_f32_e32 v19, 1.0, v211
	v_fma_f32 v12, v12, v16, v176
	v_fma_f32 v13, v13, v17, v177
	v_fma_f32 v14, v14, v18, v178
	v_fma_f32 v15, v15, v19, v179
	v_cvt_pk_bf16_f32 v20, v12, v13
	v_cvt_pk_bf16_f32 v21, v14, v15
	global_store_dwordx2 v2, v[20:21], s[26:27] offset:1024
	v_mul_f32_e32 v12, v124, v10
	v_mul_f32_e32 v13, v125, v10
	v_mul_f32_e32 v14, v126, v10
	v_mul_f32_e32 v15, v127, v10
	v_mul_f32_e32 v12, v12, v92
	v_mul_f32_e32 v13, v13, v93
	v_mul_f32_e32 v14, v14, v94
	v_mul_f32_e32 v15, v15, v95
	s_waitcnt vmcnt(11)
	v_add_f32_e32 v16, 1.0, v212
	v_add_f32_e32 v17, 1.0, v213
	v_add_f32_e32 v18, 1.0, v214
	v_add_f32_e32 v19, 1.0, v215
	v_fma_f32 v12, v12, v16, v180
	v_fma_f32 v13, v13, v17, v181
	v_fma_f32 v14, v14, v18, v182
	v_fma_f32 v15, v15, v19, v183
	v_cvt_pk_bf16_f32 v22, v12, v13
	v_cvt_pk_bf16_f32 v23, v14, v15
	global_store_dwordx2 v2, v[22:23], s[26:27] offset:1536
	v_mul_f32_e32 v12, v128, v10
	v_mul_f32_e32 v13, v129, v10
	v_mul_f32_e32 v14, v130, v10
	v_mul_f32_e32 v15, v131, v10
	v_mul_f32_e32 v12, v12, v96
	v_mul_f32_e32 v13, v13, v97
	v_mul_f32_e32 v14, v14, v98
	v_mul_f32_e32 v15, v15, v99
	s_waitcnt vmcnt(10)
	v_add_f32_e32 v16, 1.0, v216
	v_add_f32_e32 v17, 1.0, v217
	v_add_f32_e32 v18, 1.0, v218
	v_add_f32_e32 v19, 1.0, v219
	v_fma_f32 v12, v12, v16, v184
	v_fma_f32 v13, v13, v17, v185
	v_fma_f32 v14, v14, v18, v186
	v_fma_f32 v15, v15, v19, v187
	v_cvt_pk_bf16_f32 v20, v12, v13
	v_cvt_pk_bf16_f32 v21, v14, v15
	global_store_dwordx2 v2, v[20:21], s[26:27] offset:2048
	v_mul_f32_e32 v12, v132, v10
	v_mul_f32_e32 v13, v133, v10
	v_mul_f32_e32 v14, v134, v10
	v_mul_f32_e32 v15, v135, v10
	v_mul_f32_e32 v12, v12, v100
	v_mul_f32_e32 v13, v13, v101
	v_mul_f32_e32 v14, v14, v102
	v_mul_f32_e32 v15, v15, v103
	s_waitcnt vmcnt(9)
	v_add_f32_e32 v16, 1.0, v220
	v_add_f32_e32 v17, 1.0, v221
	v_add_f32_e32 v18, 1.0, v222
	v_add_f32_e32 v19, 1.0, v223
	v_fma_f32 v12, v12, v16, v188
	v_fma_f32 v13, v13, v17, v189
	v_fma_f32 v14, v14, v18, v190
	v_fma_f32 v15, v15, v19, v191
	v_cvt_pk_bf16_f32 v22, v12, v13
	v_cvt_pk_bf16_f32 v23, v14, v15
	global_store_dwordx2 v2, v[22:23], s[26:27] offset:2560
	v_mul_f32_e32 v12, v136, v10
	v_mul_f32_e32 v13, v137, v10
	v_mul_f32_e32 v14, v138, v10
	v_mul_f32_e32 v15, v139, v10
	v_mul_f32_e32 v12, v12, v104
	v_mul_f32_e32 v13, v13, v105
	v_mul_f32_e32 v14, v14, v106
	v_mul_f32_e32 v15, v15, v107
	s_waitcnt vmcnt(8)
	v_add_f32_e32 v16, 1.0, v224
	v_add_f32_e32 v17, 1.0, v225
	v_add_f32_e32 v18, 1.0, v226
	v_add_f32_e32 v19, 1.0, v227
	v_fma_f32 v12, v12, v16, v192
	v_fma_f32 v13, v13, v17, v193
	v_fma_f32 v14, v14, v18, v194
	v_fma_f32 v15, v15, v19, v195
	v_cvt_pk_bf16_f32 v20, v12, v13
	v_cvt_pk_bf16_f32 v21, v14, v15
	global_store_dwordx2 v2, v[20:21], s[26:27] offset:3072
	v_mul_f32_e32 v12, v140, v10
	v_mul_f32_e32 v13, v141, v10
	v_mul_f32_e32 v14, v142, v10
	v_mul_f32_e32 v15, v143, v10
	v_mul_f32_e32 v12, v12, v108
	v_mul_f32_e32 v13, v13, v109
	v_mul_f32_e32 v14, v14, v110
	v_mul_f32_e32 v15, v15, v111
	s_waitcnt vmcnt(7)
; DI void norm0_phase(const P& p, unsigned char* smem) {
;     ...
; #pragma unroll
;         for (int i = 0; i < 8; ++i) {
;             const int j = i * 256 + lane * 4;
;             const f32x4 gw = *(const f32x4*)(p.norm_pre + j), sh = *(const f32x4*)(md + j), scl = *(const f32x4*)(md + 2048 + j);
;             float o[4];
; #pragma unroll
;             for (int e = 0; e < 4; ++e) o[e] = v[i][e] * rstd * gw[e] * (1.f + scl[e]) + sh[e];
;             u32x2 w; w.x = pk2(o[0], o[1]); w.y = pk2(o[2], o[3]);
;             *(u32x2*)(nb + (size_t)row * DM + j) = w;
;         }
	v_add_f32_e32 v16, 1.0, v228
	v_add_f32_e32 v17, 1.0, v229
	v_add_f32_e32 v18, 1.0, v230
	v_add_f32_e32 v19, 1.0, v231
	v_fma_f32 v12, v12, v16, v196
	v_fma_f32 v13, v13, v17, v197
	v_fma_f32 v14, v14, v18, v198
	v_fma_f32 v15, v15, v19, v199
	v_cvt_pk_bf16_f32 v22, v12, v13
	v_cvt_pk_bf16_f32 v23, v14, v15
	global_store_dwordx2 v2, v[22:23], s[26:27] offset:3584
	v_mul_f32_e32 v12, v144, v11
	v_mul_f32_e32 v13, v145, v11
	v_mul_f32_e32 v14, v146, v11
	v_mul_f32_e32 v15, v147, v11
	v_mul_f32_e32 v12, v12, v80
	v_mul_f32_e32 v13, v13, v81
	v_mul_f32_e32 v14, v14, v82
	v_mul_f32_e32 v15, v15, v83
	v_add_f32_e32 v16, 1.0, v200
	v_add_f32_e32 v17, 1.0, v201
	v_add_f32_e32 v18, 1.0, v202
	v_add_f32_e32 v19, 1.0, v203
	v_fma_f32 v12, v12, v16, v168
	v_fma_f32 v13, v13, v17, v169
	v_fma_f32 v14, v14, v18, v170
	v_fma_f32 v15, v15, v19, v171
	v_cvt_pk_bf16_f32 v20, v12, v13
	v_cvt_pk_bf16_f32 v21, v14, v15
	global_store_dwordx2 v3, v[20:21], s[26:27] offset:0
	v_mul_f32_e32 v12, v148, v11
	v_mul_f32_e32 v13, v149, v11
	v_mul_f32_e32 v14, v150, v11
	v_mul_f32_e32 v15, v151, v11
	v_mul_f32_e32 v12, v12, v84
	v_mul_f32_e32 v13, v13, v85
	v_mul_f32_e32 v14, v14, v86
	v_mul_f32_e32 v15, v15, v87
	v_add_f32_e32 v16, 1.0, v204
	v_add_f32_e32 v17, 1.0, v205
	v_add_f32_e32 v18, 1.0, v206
	v_add_f32_e32 v19, 1.0, v207
	v_fma_f32 v12, v12, v16, v172
	v_fma_f32 v13, v13, v17, v173
	v_fma_f32 v14, v14, v18, v174
	v_fma_f32 v15, v15, v19, v175
	v_cvt_pk_bf16_f32 v22, v12, v13
	v_cvt_pk_bf16_f32 v23, v14, v15
	global_store_dwordx2 v3, v[22:23], s[26:27] offset:512
	v_mul_f32_e32 v12, v152, v11
	v_mul_f32_e32 v13, v153, v11
	v_mul_f32_e32 v14, v154, v11
	v_mul_f32_e32 v15, v155, v11
	v_mul_f32_e32 v12, v12, v88
	v_mul_f32_e32 v13, v13, v89
	v_mul_f32_e32 v14, v14, v90
	v_mul_f32_e32 v15, v15, v91
	v_add_f32_e32 v16, 1.0, v208
	v_add_f32_e32 v17, 1.0, v209
	v_add_f32_e32 v18, 1.0, v210
	v_add_f32_e32 v19, 1.0, v211
	v_fma_f32 v12, v12, v16, v176
	v_fma_f32 v13, v13, v17, v177
	v_fma_f32 v14, v14, v18, v178
	v_fma_f32 v15, v15, v19, v179
	v_cvt_pk_bf16_f32 v20, v12, v13
	v_cvt_pk_bf16_f32 v21, v14, v15
	global_store_dwordx2 v3, v[20:21], s[26:27] offset:1024
	v_mul_f32_e32 v12, v156, v11
	v_mul_f32_e32 v13, v157, v11
	v_mul_f32_e32 v14, v158, v11
	v_mul_f32_e32 v15, v159, v11
	v_mul_f32_e32 v12, v12, v92
	v_mul_f32_e32 v13, v13, v93
	v_mul_f32_e32 v14, v14, v94
	v_mul_f32_e32 v15, v15, v95
	v_add_f32_e32 v16, 1.0, v212
	v_add_f32_e32 v17, 1.0, v213
	v_add_f32_e32 v18, 1.0, v214
	v_add_f32_e32 v19, 1.0, v215
	v_fma_f32 v12, v12, v16, v180
	v_fma_f32 v13, v13, v17, v181
	v_fma_f32 v14, v14, v18, v182
	v_fma_f32 v15, v15, v19, v183
	v_cvt_pk_bf16_f32 v22, v12, v13
	v_cvt_pk_bf16_f32 v23, v14, v15
	global_store_dwordx2 v3, v[22:23], s[26:27] offset:1536
	v_mul_f32_e32 v12, v160, v11
	v_mul_f32_e32 v13, v161, v11
	v_mul_f32_e32 v14, v162, v11
	v_mul_f32_e32 v15, v163, v11
	v_mul_f32_e32 v12, v12, v96
	v_mul_f32_e32 v13, v13, v97
	v_mul_f32_e32 v14, v14, v98
	v_mul_f32_e32 v15, v15, v99
	v_add_f32_e32 v16, 1.0, v216
	v_add_f32_e32 v17, 1.0, v217
	v_add_f32_e32 v18, 1.0, v218
	v_add_f32_e32 v19, 1.0, v219
	v_fma_f32 v12, v12, v16, v184
	v_fma_f32 v13, v13, v17, v185
	v_fma_f32 v14, v14, v18, v186
	v_fma_f32 v15, v15, v19, v187
	v_cvt_pk_bf16_f32 v20, v12, v13
	v_cvt_pk_bf16_f32 v21, v14, v15
	global_store_dwordx2 v3, v[20:21], s[26:27] offset:2048
	v_mul_f32_e32 v12, v232, v11
	v_mul_f32_e32 v13, v233, v11
	v_mul_f32_e32 v14, v234, v11
	v_mul_f32_e32 v15, v235, v11
	v_mul_f32_e32 v12, v12, v100
	v_mul_f32_e32 v13, v13, v101
	v_mul_f32_e32 v14, v14, v102
	v_mul_f32_e32 v15, v15, v103
	v_add_f32_e32 v16, 1.0, v220
	v_add_f32_e32 v17, 1.0, v221
	v_add_f32_e32 v18, 1.0, v222
	v_add_f32_e32 v19, 1.0, v223
	v_fma_f32 v12, v12, v16, v188
	v_fma_f32 v13, v13, v17, v189
	v_fma_f32 v14, v14, v18, v190
	v_fma_f32 v15, v15, v19, v191
	v_cvt_pk_bf16_f32 v22, v12, v13
	v_cvt_pk_bf16_f32 v23, v14, v15
	global_store_dwordx2 v3, v[22:23], s[26:27] offset:2560
	v_mul_f32_e32 v12, v236, v11
	v_mul_f32_e32 v13, v237, v11
	v_mul_f32_e32 v14, v238, v11
	v_mul_f32_e32 v15, v239, v11
	v_mul_f32_e32 v12, v12, v104
	v_mul_f32_e32 v13, v13, v105
	v_mul_f32_e32 v14, v14, v106
	v_mul_f32_e32 v15, v15, v107
	v_add_f32_e32 v16, 1.0, v224
	v_add_f32_e32 v17, 1.0, v225
	v_add_f32_e32 v18, 1.0, v226
	v_add_f32_e32 v19, 1.0, v227
	v_fma_f32 v12, v12, v16, v192
	v_fma_f32 v13, v13, v17, v193
	v_fma_f32 v14, v14, v18, v194
	v_fma_f32 v15, v15, v19, v195
	v_cvt_pk_bf16_f32 v20, v12, v13
	v_cvt_pk_bf16_f32 v21, v14, v15
	global_store_dwordx2 v3, v[20:21], s[26:27] offset:3072
	v_mul_f32_e32 v12, v240, v11
	v_mul_f32_e32 v13, v241, v11
	v_mul_f32_e32 v14, v242, v11
	v_mul_f32_e32 v15, v243, v11
	v_mul_f32_e32 v12, v12, v108
	v_mul_f32_e32 v13, v13, v109
	v_mul_f32_e32 v14, v14, v110
	v_mul_f32_e32 v15, v15, v111
	v_add_f32_e32 v16, 1.0, v228
	v_add_f32_e32 v17, 1.0, v229
	v_add_f32_e32 v18, 1.0, v230
	v_add_f32_e32 v19, 1.0, v231
	v_fma_f32 v12, v12, v16, v196
	v_fma_f32 v13, v13, v17, v197
	v_fma_f32 v14, v14, v18, v198
	v_fma_f32 v15, v15, v19, v199
	v_cvt_pk_bf16_f32 v22, v12, v13
	v_cvt_pk_bf16_f32 v23, v14, v15
	global_store_dwordx2 v3, v[22:23], s[26:27] offset:3584

; DI int otid() { int t = threadIdx.x; asm volatile("" : "+v"(t)); return t; }
; DI void finish_item(const P& p, int l, int r16) {
;     const bf16_t* S = (const bf16_t*)(p.ws + WS_SBUF);
;     bf16_t* Y = (bf16_t*)(p.ws + WS_YBUF);
;     const bf16_t* O = (const bf16_t*)(p.ws + WS_NBUF);
;     const int tid = otid(); const int row0 = r16 * 16 + (tid >> 7) * 4, u = tid & 127, mx = u >> 6, hh = (u >> 4) & 3, sub = u & 15;
;     const int chn = 128 * hh + 8 * sub;
;     u32x4 ra[4], rb[4], rg[4];
; #pragma unroll
;     for (int k = 0; k < 4; ++k) {
;         ra[k] = __builtin_nontemporal_load((const u32x4*)(O + ((size_t)(mx * 2 + 0) * NROW + row0 + k) * 512 + chn));
;         rb[k] = __builtin_nontemporal_load((const u32x4*)(O + ((size_t)(mx * 2 + 1) * NROW + row0 + k) * 512 + chn));
;         rg[k] = __builtin_nontemporal_load((const u32x4*)(S + (size_t)(row0 + k) * NP + (mx ? C_GDN_G : C_GLA_G) + chn));
;     }
;     const float* nwp = (mx ? p.gdn_norm : p.gla_norm) + l * 128 + 8 * sub;
;     const f32x4 nw0 = *(const f32x4*)nwp, nw1 = *(const f32x4*)(nwp + 4);
.LBB0_679:
	s_or_b64 exec, exec, s[0:1]
	s_mov_b64 s[0:1], 0
	s_waitcnt lgkmcnt(0)
	s_barrier
	s_mov_b32 s0, s19
	v_readlane_b32 s4, v254, 26
	v_readlane_b32 s0, v252, 1
	v_readlane_b32 s1, v252, 2
	s_and_b64 s[0:1], s[0:1], exec
	s_movk_i32 s0, 0x240
	v_readlane_b32 s21, v253, 0
	s_cselect_b32 s22, s0, 0x200
	v_readlane_b32 s7, v254, 29
	v_readlane_b32 s36, v254, 39
	s_cmp_ge_i32 s21, s22
	v_readlane_b32 s5, v254, 27
	v_readlane_b32 s6, v254, 28
	s_movk_i32 s7, 0x3800
	s_mov_b64 s[8:9], 0x6c3c000
	s_brev_b32 s10, 60
	v_readlane_b32 s40, v254, 43
	v_readlane_b32 s41, v254, 44
	v_readlane_b32 s48, v254, 51
	v_readlane_b32 s49, v254, 52
	v_readlane_b32 s37, v254, 40
	v_readlane_b32 s38, v254, 41
	v_readlane_b32 s39, v254, 42
	v_readlane_b32 s42, v254, 45
	v_readlane_b32 s43, v254, 46
	v_readlane_b32 s44, v254, 47
	v_readlane_b32 s45, v254, 48
	v_readlane_b32 s46, v254, 49
	v_readlane_b32 s47, v254, 50
	v_readlane_b32 s50, v254, 53
	v_readlane_b32 s51, v254, 54
	s_cbranch_scc1 .LBB0_682
	v_lshrrev_b32_e32 v118, 7, v166
	v_and_b32_e32 v119, 0x7f, v166
	v_lshrrev_b32_e32 v120, 6, v119
	v_and_b32_e32 v121, 63, v119
	v_lshlrev_b32_e32 v121, 4, v121
	v_lshlrev_b32_e32 v104, 24, v120
	v_lshl_add_u32 v104, v120, 21, v104
	v_lshl_add_u32 v104, v118, 12, v104
	v_add_u32_e32 v104, v104, v121
	v_add_u32_e32 v104, 0x483c000, v104
	v_add_u32_e32 v105, 0x900000, v104
	v_mul_u32_u24_e32 v106, 0xe000, v118
	v_lshl_add_u32 v106, v120, 12, v106
	v_add_u32_e32 v106, v106, v121
	v_add_u32_e32 v106, 0x6c3c800, v106
	v_add_u32_e32 v107, 0x3800, v106
	v_add_u32_e32 v108, 0x7000, v106
	v_add_u32_e32 v109, 0xa800, v106
	v_lshlrev_b32_e32 v110, 14, v118
	v_lshl_add_u32 v110, v120, 10, v110
	v_add_u32_e32 v110, v110, v121
	v_add_u32_e32 v110, 0xea3c000, v110
	v_add_u32_e32 v111, 0x1000, v110
	v_add_u32_e32 v112, 0x2000, v110
	v_add_u32_e32 v113, 0x3000, v110
	v_and_b32_e32 v122, 63, v166
	v_xor_b32_e32 v114, 1, v122
	v_lshlrev_b32_e32 v114, 2, v114
	v_xor_b32_e32 v115, 2, v122
	v_lshlrev_b32_e32 v115, 2, v115
	v_xor_b32_e32 v116, 4, v122
	v_lshlrev_b32_e32 v116, 2, v116
	v_xor_b32_e32 v117, 8, v122
	v_lshlrev_b32_e32 v117, 2, v117
	v_and_b32_e32 v123, 15, v119
	v_lshlrev_b32_e32 v123, 5, v123
	s_lshl_b32 s0, s12, 9
	v_add_u32_e32 v123, s0, v123
	v_cmp_eq_u32_e32 vcc, 0, v120
	s_and_saveexec_b64 s[2:3], vcc
	global_load_dwordx4 v[96:99], v123, s[40:41]
	global_load_dwordx4 v[100:103], v123, s[40:41] offset:16
	s_andn2_b64 exec, s[2:3], exec
	global_load_dwordx4 v[96:99], v123, s[48:49]
	global_load_dwordx4 v[100:103], v123, s[48:49] offset:16
	s_mov_b64 exec, s[2:3]
	v_mov_b32_e32 v124, 0x358637bd
	v_mov_b32_e32 v125, 0xbfb8aa3b
	s_mov_b32 s24, s21
	s_lshl_b32 s0, s24, 14
	s_add_u32 s36, s4, s0
	s_addc_u32 s37, s5, 0
	s_mul_i32 s0, s24, 0x38000
	s_add_u32 s38, s4, s0
	s_addc_u32 s39, s5, 0
	global_load_dwordx4 v[0:3], v104, s[36:37] offset:0 nt
	global_load_dwordx4 v[16:19], v105, s[36:37] offset:0 nt
	global_load_dwordx4 v[32:35], v106, s[38:39] nt
	global_load_dwordx4 v[4:7], v104, s[36:37] offset:1024 nt
	global_load_dwordx4 v[20:23], v105, s[36:37] offset:1024 nt
	global_load_dwordx4 v[36:39], v107, s[38:39] nt
	global_load_dwordx4 v[8:11], v104, s[36:37] offset:2048 nt
	global_load_dwordx4 v[24:27], v105, s[36:37] offset:2048 nt
	global_load_dwordx4 v[40:43], v108, s[38:39] nt
	global_load_dwordx4 v[12:15], v104, s[36:37] offset:3072 nt
	global_load_dwordx4 v[28:31], v105, s[36:37] offset:3072 nt
	global_load_dwordx4 v[44:47], v109, s[38:39] nt
	s_add_u32 s7, s24, s6
	s_cmp_lt_u32 s7, s22
	s_cbranch_scc0 .Lfin_only
	s_lshl_b32 s0, s7, 14
	s_add_u32 s36, s4, s0
	s_addc_u32 s37, s5, 0
	s_mul_i32 s0, s7, 0x38000
	s_add_u32 s38, s4, s0
	s_addc_u32 s39, s5, 0
	global_load_dwordx4 v[48:51], v104, s[36:37] offset:0 nt
	global_load_dwordx4 v[64:67], v105, s[36:37] offset:0 nt
	global_load_dwordx4 v[80:83], v106, s[38:39] nt
	global_load_dwordx4 v[52:55], v104, s[36:37] offset:1024 nt
	global_load_dwordx4 v[68:71], v105, s[36:37] offset:1024 nt
	global_load_dwordx4 v[84:87], v107, s[38:39] nt
	global_load_dwordx4 v[56:59], v104, s[36:37] offset:2048 nt
	global_load_dwordx4 v[72:75], v105, s[36:37] offset:2048 nt
	global_load_dwordx4 v[88:91], v108, s[38:39] nt
	global_load_dwordx4 v[60:63], v104, s[36:37] offset:3072 nt
	global_load_dwordx4 v[76:79], v105, s[36:37] offset:3072 nt
	global_load_dwordx4 v[92:95], v109, s[38:39] nt
	s_waitcnt vmcnt(12)
	s_branch .Lfin_first

; DI int otid() { int t = threadIdx.x; asm volatile("" : "+v"(t)); return t; }
; DI void finish_item(const P& p, int l, int r16) {
;     ...
;     const int tid = otid(); const int row0 = r16 * 16 + (tid >> 7) * 4, u = tid & 127, mx = u >> 6, hh = (u >> 4) & 3, sub = u & 15;
;     const int chn = 128 * hh + 8 * sub;
;     u32x4 ra[4], rb[4], rg[4];
; #pragma unroll
;     for (int k = 0; k < 4; ++k) {
;         ra[k] = __builtin_nontemporal_load((const u32x4*)(O + ((size_t)(mx * 2 + 0) * NROW + row0 + k) * 512 + chn));
;         rb[k] = __builtin_nontemporal_load((const u32x4*)(O + ((size_t)(mx * 2 + 1) * NROW + row0 + k) * 512 + chn));
;         rg[k] = __builtin_nontemporal_load((const u32x4*)(S + (size_t)(row0 + k) * NP + (mx ? C_GDN_G : C_GLA_G) + chn));
;     }
.Lfin_it1:
	s_cmp_lt_u32 s7, s22
	s_cbranch_scc0 .Lfin_last1
	s_lshl_b32 s0, s7, 14
	s_add_u32 s36, s4, s0
	s_addc_u32 s37, s5, 0
	s_mul_i32 s0, s7, 0x38000
	s_add_u32 s38, s4, s0
	s_addc_u32 s39, s5, 0
	global_load_dwordx4 v[0:3], v104, s[36:37] offset:0 nt
	global_load_dwordx4 v[16:19], v105, s[36:37] offset:0 nt
	global_load_dwordx4 v[32:35], v106, s[38:39] nt
	global_load_dwordx4 v[4:7], v104, s[36:37] offset:1024 nt
	global_load_dwordx4 v[20:23], v105, s[36:37] offset:1024 nt
	global_load_dwordx4 v[36:39], v107, s[38:39] nt
	global_load_dwordx4 v[8:11], v104, s[36:37] offset:2048 nt
	global_load_dwordx4 v[24:27], v105, s[36:37] offset:2048 nt
	global_load_dwordx4 v[40:43], v108, s[38:39] nt
	global_load_dwordx4 v[12:15], v104, s[36:37] offset:3072 nt
	global_load_dwordx4 v[28:31], v105, s[36:37] offset:3072 nt
	global_load_dwordx4 v[44:47], v109, s[38:39] nt
	s_waitcnt vmcnt(16)
	s_branch .Lfin_proc1
.Lfin_last1:
	s_waitcnt vmcnt(4)

; #define ITEM_BEGIN { size_t z_ = 0; asm volatile("" : "+s"(z_)); q.ws = p.ws + z_; sm = smem + osgpr(0); }
; #define PHASE_BEGIN P q = p; { size_t z_ = 0; asm volatile("" : "+s"(z_)); q.ws = p.ws + z_; } unsigned char* sm = smem + osgpr(0); const int b1 = osgpr(bid); (void)sm; (void)b1;
; DI void finish_item(const P& p, int l, int r16) {
;     ...
; #pragma unroll
;     for (int k = 0; k < 4; ++k) {
;         ra[k] = __builtin_nontemporal_load((const u32x4*)(O + ((size_t)(mx * 2 + 0) * NROW + row0 + k) * 512 + chn));
;         rb[k] = __builtin_nontemporal_load((const u32x4*)(O + ((size_t)(mx * 2 + 1) * NROW + row0 + k) * 512 + chn));
;         rg[k] = __builtin_nontemporal_load((const u32x4*)(S + (size_t)(row0 + k) * NP + (mx ? C_GDN_G : C_GLA_G) + chn));
;     }
; __global__ __launch_bounds__(512, 2) void mega(P p) {
;     ...
;         { PHASE_BEGIN const int nf = (l == 0 ? NROW : NLAT) / 16; for (int it = b1; it < nf; it += nb) { ITEM_BEGIN finish_item(q, l, it); } }
.Lfin_it0:
	s_cmp_lt_u32 s7, s22
	s_cbranch_scc0 .Lfin_last0
	s_lshl_b32 s0, s7, 14
	s_add_u32 s36, s4, s0
	s_addc_u32 s37, s5, 0
	s_mul_i32 s0, s7, 0x38000
	s_add_u32 s38, s4, s0
	s_addc_u32 s39, s5, 0
	global_load_dwordx4 v[48:51], v104, s[36:37] offset:0 nt
	global_load_dwordx4 v[64:67], v105, s[36:37] offset:0 nt
	global_load_dwordx4 v[80:83], v106, s[38:39] nt
	global_load_dwordx4 v[52:55], v104, s[36:37] offset:1024 nt
	global_load_dwordx4 v[68:71], v105, s[36:37] offset:1024 nt
	global_load_dwordx4 v[84:87], v107, s[38:39] nt
	global_load_dwordx4 v[56:59], v104, s[36:37] offset:2048 nt
	global_load_dwordx4 v[72:75], v105, s[36:37] offset:2048 nt
	global_load_dwordx4 v[88:91], v108, s[38:39] nt
	global_load_dwordx4 v[60:63], v104, s[36:37] offset:3072 nt
	global_load_dwordx4 v[76:79], v105, s[36:37] offset:3072 nt
	global_load_dwordx4 v[92:95], v109, s[38:39] nt
	s_waitcnt vmcnt(16)
	s_branch .Lfin_proc0

; DI void unpack8(u32x4 v, float* o) { o[0] = lo16(v.x); o[1] = hi16(v.x); o[2] = lo16(v.y); o[3] = hi16(v.y); o[4] = lo16(v.z); o[5] = hi16(v.z); o[6] = lo16(v.w); o[7] = hi16(v.w); }
; DI void finish_item(const P& p, int l, int r16) {
;     ...
;     for (int k = 0; k < 4; ++k) {
;         float a[8], b[8], o[8], gt[8];
;         unpack8(ra[k], a); unpack8(rb[k], b); unpack8(rg[k], gt);
;         float ss = 0.f;
; #pragma unroll
;         for (int e = 0; e < 8; ++e) { o[e] = a[e] + b[e]; ss += o[e] * o[e]; }
;         ss += __shfl_xor(ss, 1); ss += __shfl_xor(ss, 2); ss += __shfl_xor(ss, 4); ss += __shfl_xor(ss, 8);
.Lfin_proc0:
	v_and_b32_e32 v118, 0xffff0000, v0
	v_and_b32_e32 v119, 0xffff0000, v16
	v_lshlrev_b32_e32 v0, 16, v0
	v_lshlrev_b32_e32 v120, 16, v16
	v_add_f32_e32 v0, v0, v120
	v_add_f32_e32 v16, v118, v119
	v_mul_f32_e32 v142, v0, v0
	v_fmac_f32_e32 v142, v16, v16
	v_and_b32_e32 v118, 0xffff0000, v1
	v_and_b32_e32 v119, 0xffff0000, v17
	v_lshlrev_b32_e32 v1, 16, v1
	v_lshlrev_b32_e32 v120, 16, v17
	v_add_f32_e32 v1, v1, v120
	v_add_f32_e32 v17, v118, v119
	v_fmac_f32_e32 v142, v1, v1
	v_fmac_f32_e32 v142, v17, v17
	v_and_b32_e32 v118, 0xffff0000, v2
	v_and_b32_e32 v119, 0xffff0000, v18
	v_lshlrev_b32_e32 v2, 16, v2
	v_lshlrev_b32_e32 v120, 16, v18
	v_add_f32_e32 v2, v2, v120
	v_add_f32_e32 v18, v118, v119
	v_fmac_f32_e32 v142, v2, v2
	v_fmac_f32_e32 v142, v18, v18
	v_and_b32_e32 v118, 0xffff0000, v3
	v_and_b32_e32 v119, 0xffff0000, v19
	v_lshlrev_b32_e32 v3, 16, v3
	v_lshlrev_b32_e32 v120, 16, v19
	v_add_f32_e32 v3, v3, v120
	v_add_f32_e32 v19, v118, v119
	v_fmac_f32_e32 v142, v3, v3
	v_fmac_f32_e32 v142, v19, v19
	v_and_b32_e32 v118, 0xffff0000, v4
	v_and_b32_e32 v119, 0xffff0000, v20
	v_lshlrev_b32_e32 v4, 16, v4
	v_lshlrev_b32_e32 v120, 16, v20
	v_add_f32_e32 v4, v4, v120
	v_add_f32_e32 v20, v118, v119
	v_mul_f32_e32 v143, v4, v4
	v_fmac_f32_e32 v143, v20, v20
	v_and_b32_e32 v118, 0xffff0000, v5
	v_and_b32_e32 v119, 0xffff0000, v21
	v_lshlrev_b32_e32 v5, 16, v5
	v_lshlrev_b32_e32 v120, 16, v21
	v_add_f32_e32 v5, v5, v120
	v_add_f32_e32 v21, v118, v119
	v_fmac_f32_e32 v143, v5, v5
	v_fmac_f32_e32 v143, v21, v21
	v_and_b32_e32 v118, 0xffff0000, v6
	v_and_b32_e32 v119, 0xffff0000, v22
	v_lshlrev_b32_e32 v6, 16, v6
	v_lshlrev_b32_e32 v120, 16, v22
	v_add_f32_e32 v6, v6, v120
	v_add_f32_e32 v22, v118, v119
	v_fmac_f32_e32 v143, v6, v6
	v_fmac_f32_e32 v143, v22, v22
	v_and_b32_e32 v118, 0xffff0000, v7
	v_and_b32_e32 v119, 0xffff0000, v23
	v_lshlrev_b32_e32 v7, 16, v7
	v_lshlrev_b32_e32 v120, 16, v23
	v_add_f32_e32 v7, v7, v120
	v_add_f32_e32 v23, v118, v119
	v_fmac_f32_e32 v143, v7, v7
	v_fmac_f32_e32 v143, v23, v23
	v_and_b32_e32 v118, 0xffff0000, v8
	v_and_b32_e32 v119, 0xffff0000, v24
	v_lshlrev_b32_e32 v8, 16, v8
	v_lshlrev_b32_e32 v120, 16, v24
	v_add_f32_e32 v8, v8, v120
	v_add_f32_e32 v24, v118, v119
	v_mul_f32_e32 v144, v8, v8
	v_fmac_f32_e32 v144, v24, v24
	v_and_b32_e32 v118, 0xffff0000, v9
	v_and_b32_e32 v119, 0xffff0000, v25
	v_lshlrev_b32_e32 v9, 16, v9
	v_lshlrev_b32_e32 v120, 16, v25
	v_add_f32_e32 v9, v9, v120
	v_add_f32_e32 v25, v118, v119
	v_fmac_f32_e32 v144, v9, v9
	v_fmac_f32_e32 v144, v25, v25
	v_and_b32_e32 v118, 0xffff0000, v10
	v_and_b32_e32 v119, 0xffff0000, v26
	v_lshlrev_b32_e32 v10, 16, v10
	v_lshlrev_b32_e32 v120, 16, v26
	v_add_f32_e32 v10, v10, v120
	v_add_f32_e32 v26, v118, v119
	v_fmac_f32_e32 v144, v10, v10
	v_fmac_f32_e32 v144, v26, v26
	v_and_b32_e32 v118, 0xffff0000, v11
	v_and_b32_e32 v119, 0xffff0000, v27
	v_lshlrev_b32_e32 v11, 16, v11
	v_lshlrev_b32_e32 v120, 16, v27
	v_add_f32_e32 v11, v11, v120
	v_add_f32_e32 v27, v118, v119
	v_fmac_f32_e32 v144, v11, v11
	v_fmac_f32_e32 v144, v27, v27
	v_and_b32_e32 v118, 0xffff0000, v12
	v_and_b32_e32 v119, 0xffff0000, v28
	v_lshlrev_b32_e32 v12, 16, v12
	v_lshlrev_b32_e32 v120, 16, v28
	v_add_f32_e32 v12, v12, v120
	v_add_f32_e32 v28, v118, v119
	v_mul_f32_e32 v145, v12, v12
	v_fmac_f32_e32 v145, v28, v28
	v_and_b32_e32 v118, 0xffff0000, v13
	v_and_b32_e32 v119, 0xffff0000, v29
	v_lshlrev_b32_e32 v13, 16, v13
	v_lshlrev_b32_e32 v120, 16, v29
	v_add_f32_e32 v13, v13, v120
	v_add_f32_e32 v29, v118, v119
	v_fmac_f32_e32 v145, v13, v13
	v_fmac_f32_e32 v145, v29, v29
	v_and_b32_e32 v118, 0xffff0000, v14
	v_and_b32_e32 v119, 0xffff0000, v30
	v_lshlrev_b32_e32 v14, 16, v14
	v_lshlrev_b32_e32 v120, 16, v30
	v_add_f32_e32 v14, v14, v120
	v_add_f32_e32 v30, v118, v119
	v_fmac_f32_e32 v145, v14, v14
	v_fmac_f32_e32 v145, v30, v30
	v_and_b32_e32 v118, 0xffff0000, v15
	v_and_b32_e32 v119, 0xffff0000, v31
	v_lshlrev_b32_e32 v15, 16, v15
	v_lshlrev_b32_e32 v120, 16, v31
	v_add_f32_e32 v15, v15, v120
	v_add_f32_e32 v31, v118, v119
	v_fmac_f32_e32 v145, v15, v15
	v_fmac_f32_e32 v145, v31, v31
	ds_bpermute_b32 v146, v114, v142
	ds_bpermute_b32 v147, v114, v143
	ds_bpermute_b32 v148, v114, v144
	ds_bpermute_b32 v149, v114, v145
	s_waitcnt lgkmcnt(3)
	v_add_f32_e32 v142, v142, v146
	s_waitcnt lgkmcnt(2)
	v_add_f32_e32 v143, v143, v147
	s_waitcnt lgkmcnt(1)
	v_add_f32_e32 v144, v144, v148
	s_waitcnt lgkmcnt(0)
	v_add_f32_e32 v145, v145, v149
	ds_bpermute_b32 v146, v115, v142
	ds_bpermute_b32 v147, v115, v143
	ds_bpermute_b32 v148, v115, v144
	ds_bpermute_b32 v149, v115, v145
	s_waitcnt lgkmcnt(3)
	v_add_f32_e32 v142, v142, v146
	s_waitcnt lgkmcnt(2)
	v_add_f32_e32 v143, v143, v147
	s_waitcnt lgkmcnt(1)
	v_add_f32_e32 v144, v144, v148
	s_waitcnt lgkmcnt(0)
	v_add_f32_e32 v145, v145, v149
	ds_bpermute_b32 v146, v116, v142
	ds_bpermute_b32 v147, v116, v143
	ds_bpermute_b32 v148, v116, v144
	ds_bpermute_b32 v149, v116, v145
	s_waitcnt lgkmcnt(3)
	v_add_f32_e32 v142, v142, v146
	s_waitcnt lgkmcnt(2)
	v_add_f32_e32 v143, v143, v147
	s_waitcnt lgkmcnt(1)
	v_add_f32_e32 v144, v144, v148
	s_waitcnt lgkmcnt(0)
	v_add_f32_e32 v145, v145, v149
	ds_bpermute_b32 v146, v117, v142
	ds_bpermute_b32 v147, v117, v143
	ds_bpermute_b32 v148, v117, v144
	ds_bpermute_b32 v149, v117, v145
	s_waitcnt lgkmcnt(3)
	v_add_f32_e32 v142, v142, v146
	s_waitcnt lgkmcnt(2)
	v_add_f32_e32 v143, v143, v147
	s_waitcnt lgkmcnt(1)
	v_add_f32_e32 v144, v144, v148
	s_waitcnt lgkmcnt(0)
; DI u32x4 pack8(const float* o) { u32x4 r; r.x = pk2(o[0], o[1]); r.y = pk2(o[2], o[3]); r.z = pk2(o[4], o[5]); r.w = pk2(o[6], o[7]); return r; }
; DI float siluf(float x) { return x * __builtin_amdgcn_rcpf(1.f + __expf(-x)); }
; DI void finish_item(const P& p, int l, int r16) {
;     ...
;         const float rstd = rsqrtf(ss * (1.f / 128.f) + 1e-6f);
; #pragma unroll
;         for (int e = 0; e < 8; ++e) o[e] = o[e] * rstd * (e < 4 ? nw0[e & 3] : nw1[e & 3]) * siluf(gt[e]);
;         *(u32x4*)(Y + (size_t)(row0 + k) * DM + 512 * mx + chn) = pack8(o);
	v_add_f32_e32 v145, v145, v149
	v_fmamk_f32 v142, v142, 0x3c000000, v124
	v_fmamk_f32 v143, v143, 0x3c000000, v124
	v_fmamk_f32 v144, v144, 0x3c000000, v124
	v_fmamk_f32 v145, v145, 0x3c000000, v124
	v_rsq_f32_e32 v150, v142
	v_rsq_f32_e32 v151, v143
	v_rsq_f32_e32 v152, v144
	v_rsq_f32_e32 v153, v145
	s_lshl_b32 s0, s24, 16
	s_add_u32 s42, s4, s0
	s_addc_u32 s43, s5, 0
	v_lshlrev_b32_e32 v118, 16, v32
	v_and_b32_e32 v119, 0xffff0000, v32
	v_mul_f32_e32 v120, v125, v118
	v_mul_f32_e32 v121, v125, v119
	v_exp_f32_e32 v120, v120
	v_exp_f32_e32 v121, v121
	v_mul_f32_e32 v0, v0, v150
	v_add_f32_e32 v120, 1.0, v120
	v_add_f32_e32 v121, 1.0, v121
	v_rcp_f32_e32 v120, v120
	v_rcp_f32_e32 v121, v121
	v_mul_f32_e32 v16, v16, v150
	v_mul_f32_e32 v0, v0, v96
	v_mul_f32_e32 v118, v118, v120
	v_mul_f32_e32 v119, v119, v121
	v_mul_f32_e32 v16, v16, v97
	v_mul_f32_e32 v0, v0, v118
	v_mul_f32_e32 v16, v16, v119
	v_cvt_pk_bf16_f32 v154, v0, v16
	v_lshlrev_b32_e32 v118, 16, v33
	v_and_b32_e32 v119, 0xffff0000, v33
	v_mul_f32_e32 v120, v125, v118
	v_mul_f32_e32 v121, v125, v119
	v_exp_f32_e32 v120, v120
	v_exp_f32_e32 v121, v121
	v_mul_f32_e32 v1, v1, v150
	v_add_f32_e32 v120, 1.0, v120
	v_add_f32_e32 v121, 1.0, v121
	v_rcp_f32_e32 v120, v120
	v_rcp_f32_e32 v121, v121
	v_mul_f32_e32 v17, v17, v150
	v_mul_f32_e32 v1, v1, v98
	v_mul_f32_e32 v118, v118, v120
	v_mul_f32_e32 v119, v119, v121
	v_mul_f32_e32 v17, v17, v99
	v_mul_f32_e32 v1, v1, v118
	v_mul_f32_e32 v17, v17, v119
	v_cvt_pk_bf16_f32 v155, v1, v17
	v_lshlrev_b32_e32 v118, 16, v34
	v_and_b32_e32 v119, 0xffff0000, v34
	v_mul_f32_e32 v120, v125, v118
	v_mul_f32_e32 v121, v125, v119
	v_exp_f32_e32 v120, v120
	v_exp_f32_e32 v121, v121
	v_mul_f32_e32 v2, v2, v150
	v_add_f32_e32 v120, 1.0, v120
	v_add_f32_e32 v121, 1.0, v121
	v_rcp_f32_e32 v120, v120
	v_rcp_f32_e32 v121, v121
	v_mul_f32_e32 v18, v18, v150
	v_mul_f32_e32 v2, v2, v100
	v_mul_f32_e32 v118, v118, v120
	v_mul_f32_e32 v119, v119, v121
	v_mul_f32_e32 v18, v18, v101
	v_mul_f32_e32 v2, v2, v118
	v_mul_f32_e32 v18, v18, v119
	v_cvt_pk_bf16_f32 v156, v2, v18
	v_lshlrev_b32_e32 v118, 16, v35
	v_and_b32_e32 v119, 0xffff0000, v35
	v_mul_f32_e32 v120, v125, v118
	v_mul_f32_e32 v121, v125, v119
	v_exp_f32_e32 v120, v120
	v_exp_f32_e32 v121, v121
	v_mul_f32_e32 v3, v3, v150
	v_add_f32_e32 v120, 1.0, v120
	v_add_f32_e32 v121, 1.0, v121
	v_rcp_f32_e32 v120, v120
	v_rcp_f32_e32 v121, v121
	v_mul_f32_e32 v19, v19, v150
	v_mul_f32_e32 v3, v3, v102
	v_mul_f32_e32 v118, v118, v120
	v_mul_f32_e32 v119, v119, v121
	v_mul_f32_e32 v19, v19, v103
	v_mul_f32_e32 v3, v3, v118
	v_mul_f32_e32 v19, v19, v119
	v_cvt_pk_bf16_f32 v157, v3, v19
	global_store_dwordx4 v110, v[154:157], s[42:43] sc1
	v_lshlrev_b32_e32 v118, 16, v36
	v_and_b32_e32 v119, 0xffff0000, v36
	v_mul_f32_e32 v120, v125, v118
	v_mul_f32_e32 v121, v125, v119
	v_exp_f32_e32 v120, v120
	v_exp_f32_e32 v121, v121
	v_mul_f32_e32 v4, v4, v151
	v_add_f32_e32 v120, 1.0, v120
	v_add_f32_e32 v121, 1.0, v121
	v_rcp_f32_e32 v120, v120
	v_rcp_f32_e32 v121, v121
	v_mul_f32_e32 v20, v20, v151
	v_mul_f32_e32 v4, v4, v96
	v_mul_f32_e32 v118, v118, v120
	v_mul_f32_e32 v119, v119, v121
	v_mul_f32_e32 v20, v20, v97
	v_mul_f32_e32 v4, v4, v118
	v_mul_f32_e32 v20, v20, v119
	v_cvt_pk_bf16_f32 v158, v4, v20
	v_lshlrev_b32_e32 v118, 16, v37
	v_and_b32_e32 v119, 0xffff0000, v37
	v_mul_f32_e32 v120, v125, v118
	v_mul_f32_e32 v121, v125, v119
	v_exp_f32_e32 v120, v120
	v_exp_f32_e32 v121, v121
	v_mul_f32_e32 v5, v5, v151
	v_add_f32_e32 v120, 1.0, v120
	v_add_f32_e32 v121, 1.0, v121
	v_rcp_f32_e32 v120, v120
	v_rcp_f32_e32 v121, v121
	v_mul_f32_e32 v21, v21, v151
	v_mul_f32_e32 v5, v5, v98
	v_mul_f32_e32 v118, v118, v120
	v_mul_f32_e32 v119, v119, v121
	v_mul_f32_e32 v21, v21, v99
	v_mul_f32_e32 v5, v5, v118
	v_mul_f32_e32 v21, v21, v119
	v_cvt_pk_bf16_f32 v159, v5, v21
	v_lshlrev_b32_e32 v118, 16, v38
	v_and_b32_e32 v119, 0xffff0000, v38
	v_mul_f32_e32 v120, v125, v118
	v_mul_f32_e32 v121, v125, v119
	v_exp_f32_e32 v120, v120
	v_exp_f32_e32 v121, v121
	v_mul_f32_e32 v6, v6, v151
	v_add_f32_e32 v120, 1.0, v120
	v_add_f32_e32 v121, 1.0, v121
	v_rcp_f32_e32 v120, v120
	v_rcp_f32_e32 v121, v121
	v_mul_f32_e32 v22, v22, v151
	v_mul_f32_e32 v6, v6, v100
	v_mul_f32_e32 v118, v118, v120
	v_mul_f32_e32 v119, v119, v121
	v_mul_f32_e32 v22, v22, v101
	v_mul_f32_e32 v6, v6, v118
	v_mul_f32_e32 v22, v22, v119
	v_cvt_pk_bf16_f32 v160, v6, v22
	v_lshlrev_b32_e32 v118, 16, v39
	v_and_b32_e32 v119, 0xffff0000, v39
	v_mul_f32_e32 v120, v125, v118
	v_mul_f32_e32 v121, v125, v119
	v_exp_f32_e32 v120, v120
	v_exp_f32_e32 v121, v121
	v_mul_f32_e32 v7, v7, v151
	v_add_f32_e32 v120, 1.0, v120
	v_add_f32_e32 v121, 1.0, v121
	v_rcp_f32_e32 v120, v120
	v_rcp_f32_e32 v121, v121
	v_mul_f32_e32 v23, v23, v151
	v_mul_f32_e32 v7, v7, v102
	v_mul_f32_e32 v118, v118, v120
	v_mul_f32_e32 v119, v119, v121
	v_mul_f32_e32 v23, v23, v103
	v_mul_f32_e32 v7, v7, v118
; DI u32x4 pack8(const float* o) { u32x4 r; r.x = pk2(o[0], o[1]); r.y = pk2(o[2], o[3]); r.z = pk2(o[4], o[5]); r.w = pk2(o[6], o[7]); return r; }
; DI float siluf(float x) { return x * __builtin_amdgcn_rcpf(1.f + __expf(-x)); }
; #define ITEM_BEGIN { size_t z_ = 0; asm volatile("" : "+s"(z_)); q.ws = p.ws + z_; sm = smem + osgpr(0); }
; #define PHASE_BEGIN P q = p; { size_t z_ = 0; asm volatile("" : "+s"(z_)); q.ws = p.ws + z_; } unsigned char* sm = smem + osgpr(0); const int b1 = osgpr(bid); (void)sm; (void)b1;
; DI void finish_item(const P& p, int l, int r16) {
;     ...
;         for (int e = 0; e < 8; ++e) o[e] = o[e] * rstd * (e < 4 ? nw0[e & 3] : nw1[e & 3]) * siluf(gt[e]);
;         *(u32x4*)(Y + (size_t)(row0 + k) * DM + 512 * mx + chn) = pack8(o);
; __global__ __launch_bounds__(512, 2) void mega(P p) {
;     ...
;         { PHASE_BEGIN const int nf = (l == 0 ? NROW : NLAT) / 16; for (int it = b1; it < nf; it += nb) { ITEM_BEGIN finish_item(q, l, it); } }
	v_mul_f32_e32 v23, v23, v119
	v_cvt_pk_bf16_f32 v161, v7, v23
	global_store_dwordx4 v111, v[158:161], s[42:43] sc1
	v_lshlrev_b32_e32 v118, 16, v40
	v_and_b32_e32 v119, 0xffff0000, v40
	v_mul_f32_e32 v120, v125, v118
	v_mul_f32_e32 v121, v125, v119
	v_exp_f32_e32 v120, v120
	v_exp_f32_e32 v121, v121
	v_mul_f32_e32 v8, v8, v152
	v_add_f32_e32 v120, 1.0, v120
	v_add_f32_e32 v121, 1.0, v121
	v_rcp_f32_e32 v120, v120
	v_rcp_f32_e32 v121, v121
	v_mul_f32_e32 v24, v24, v152
	v_mul_f32_e32 v8, v8, v96
	v_mul_f32_e32 v118, v118, v120
	v_mul_f32_e32 v119, v119, v121
	v_mul_f32_e32 v24, v24, v97
	v_mul_f32_e32 v8, v8, v118
	v_mul_f32_e32 v24, v24, v119
	v_cvt_pk_bf16_f32 v154, v8, v24
	v_lshlrev_b32_e32 v118, 16, v41
	v_and_b32_e32 v119, 0xffff0000, v41
	v_mul_f32_e32 v120, v125, v118
	v_mul_f32_e32 v121, v125, v119
	v_exp_f32_e32 v120, v120
	v_exp_f32_e32 v121, v121
	v_mul_f32_e32 v9, v9, v152
	v_add_f32_e32 v120, 1.0, v120
	v_add_f32_e32 v121, 1.0, v121
	v_rcp_f32_e32 v120, v120
	v_rcp_f32_e32 v121, v121
	v_mul_f32_e32 v25, v25, v152
	v_mul_f32_e32 v9, v9, v98
	v_mul_f32_e32 v118, v118, v120
	v_mul_f32_e32 v119, v119, v121
	v_mul_f32_e32 v25, v25, v99
	v_mul_f32_e32 v9, v9, v118
	v_mul_f32_e32 v25, v25, v119
	v_cvt_pk_bf16_f32 v155, v9, v25
	v_lshlrev_b32_e32 v118, 16, v42
	v_and_b32_e32 v119, 0xffff0000, v42
	v_mul_f32_e32 v120, v125, v118
	v_mul_f32_e32 v121, v125, v119
	v_exp_f32_e32 v120, v120
	v_exp_f32_e32 v121, v121
	v_mul_f32_e32 v10, v10, v152
	v_add_f32_e32 v120, 1.0, v120
	v_add_f32_e32 v121, 1.0, v121
	v_rcp_f32_e32 v120, v120
	v_rcp_f32_e32 v121, v121
	v_mul_f32_e32 v26, v26, v152
	v_mul_f32_e32 v10, v10, v100
	v_mul_f32_e32 v118, v118, v120
	v_mul_f32_e32 v119, v119, v121
	v_mul_f32_e32 v26, v26, v101
	v_mul_f32_e32 v10, v10, v118
	v_mul_f32_e32 v26, v26, v119
	v_cvt_pk_bf16_f32 v156, v10, v26
	v_lshlrev_b32_e32 v118, 16, v43
	v_and_b32_e32 v119, 0xffff0000, v43
	v_mul_f32_e32 v120, v125, v118
	v_mul_f32_e32 v121, v125, v119
	v_exp_f32_e32 v120, v120
	v_exp_f32_e32 v121, v121
	v_mul_f32_e32 v11, v11, v152
	v_add_f32_e32 v120, 1.0, v120
	v_add_f32_e32 v121, 1.0, v121
	v_rcp_f32_e32 v120, v120
	v_rcp_f32_e32 v121, v121
	v_mul_f32_e32 v27, v27, v152
	v_mul_f32_e32 v11, v11, v102
	v_mul_f32_e32 v118, v118, v120
	v_mul_f32_e32 v119, v119, v121
	v_mul_f32_e32 v27, v27, v103
	v_mul_f32_e32 v11, v11, v118
	v_mul_f32_e32 v27, v27, v119
	v_cvt_pk_bf16_f32 v157, v11, v27
	global_store_dwordx4 v112, v[154:157], s[42:43] sc1
	v_lshlrev_b32_e32 v118, 16, v44
	v_and_b32_e32 v119, 0xffff0000, v44
	v_mul_f32_e32 v120, v125, v118
	v_mul_f32_e32 v121, v125, v119
	v_exp_f32_e32 v120, v120
	v_exp_f32_e32 v121, v121
	v_mul_f32_e32 v12, v12, v153
	v_add_f32_e32 v120, 1.0, v120
	v_add_f32_e32 v121, 1.0, v121
	v_rcp_f32_e32 v120, v120
	v_rcp_f32_e32 v121, v121
	v_mul_f32_e32 v28, v28, v153
	v_mul_f32_e32 v12, v12, v96
	v_mul_f32_e32 v118, v118, v120
	v_mul_f32_e32 v119, v119, v121
	v_mul_f32_e32 v28, v28, v97
	v_mul_f32_e32 v12, v12, v118
	v_mul_f32_e32 v28, v28, v119
	v_cvt_pk_bf16_f32 v158, v12, v28
	v_lshlrev_b32_e32 v118, 16, v45
	v_and_b32_e32 v119, 0xffff0000, v45
	v_mul_f32_e32 v120, v125, v118
	v_mul_f32_e32 v121, v125, v119
	v_exp_f32_e32 v120, v120
	v_exp_f32_e32 v121, v121
	v_mul_f32_e32 v13, v13, v153
	v_add_f32_e32 v120, 1.0, v120
	v_add_f32_e32 v121, 1.0, v121
	v_rcp_f32_e32 v120, v120
	v_rcp_f32_e32 v121, v121
	v_mul_f32_e32 v29, v29, v153
	v_mul_f32_e32 v13, v13, v98
	v_mul_f32_e32 v118, v118, v120
	v_mul_f32_e32 v119, v119, v121
	v_mul_f32_e32 v29, v29, v99
	v_mul_f32_e32 v13, v13, v118
	v_mul_f32_e32 v29, v29, v119
	v_cvt_pk_bf16_f32 v159, v13, v29
	v_lshlrev_b32_e32 v118, 16, v46
	v_and_b32_e32 v119, 0xffff0000, v46
	v_mul_f32_e32 v120, v125, v118
	v_mul_f32_e32 v121, v125, v119
	v_exp_f32_e32 v120, v120
	v_exp_f32_e32 v121, v121
	v_mul_f32_e32 v14, v14, v153
	v_add_f32_e32 v120, 1.0, v120
	v_add_f32_e32 v121, 1.0, v121
	v_rcp_f32_e32 v120, v120
	v_rcp_f32_e32 v121, v121
	v_mul_f32_e32 v30, v30, v153
	v_mul_f32_e32 v14, v14, v100
	v_mul_f32_e32 v118, v118, v120
	v_mul_f32_e32 v119, v119, v121
	v_mul_f32_e32 v30, v30, v101
	v_mul_f32_e32 v14, v14, v118
	v_mul_f32_e32 v30, v30, v119
	v_cvt_pk_bf16_f32 v160, v14, v30
	v_lshlrev_b32_e32 v118, 16, v47
	v_and_b32_e32 v119, 0xffff0000, v47
	v_mul_f32_e32 v120, v125, v118
	v_mul_f32_e32 v121, v125, v119
	v_exp_f32_e32 v120, v120
	v_exp_f32_e32 v121, v121
	v_mul_f32_e32 v15, v15, v153
	v_add_f32_e32 v120, 1.0, v120
	v_add_f32_e32 v121, 1.0, v121
	v_rcp_f32_e32 v120, v120
	v_rcp_f32_e32 v121, v121
	v_mul_f32_e32 v31, v31, v153
	v_mul_f32_e32 v15, v15, v102
	v_mul_f32_e32 v118, v118, v120
	v_mul_f32_e32 v119, v119, v121
	v_mul_f32_e32 v31, v31, v103
	v_mul_f32_e32 v15, v15, v118
	v_mul_f32_e32 v31, v31, v119
	v_cvt_pk_bf16_f32 v161, v15, v31
	global_store_dwordx4 v113, v[158:161], s[42:43] sc1
	s_cmp_lt_u32 s7, s22
	s_cbranch_scc0 .Lfin_done
	s_mov_b32 s24, s7
	s_add_u32 s7, s7, s6
	s_branch .Lfin_it1
